# attention step: first four MFMA gaps after the barrier left VALU-free, softmax VALU pushed into later gaps (3-4 per gap)
# speedup vs baseline: 1.0051x; 1.0029x over previous
.Lfa_loop:
	ds_read_b128 v[150:153], v212 offset:23040
	ds_read_b128 v[154:157], v212 offset:23072
	ds_read_b128 v[158:161], v212 offset:23104
	ds_read_b128 v[162:165], v212 offset:23136
	ds_read_b128 v[166:169], v212 offset:23168
	s_waitcnt lgkmcnt(4)
	v_mfma_f32_32x32x16_bf16 v[134:149], v[150:153], v[6:9], 0
	ds_read_b128 v[150:153], v212 offset:23200
	ds_read_b128 v[170:173], v213 offset:0
	s_waitcnt lgkmcnt(5)
	v_mfma_f32_32x32x16_bf16 v[134:149], v[154:157], v[10:13], v[134:149]
	ds_read_b128 v[154:157], v212 offset:23232
	ds_read_b128 v[174:177], v213 offset:2560
	s_waitcnt lgkmcnt(6)
	v_mfma_f32_32x32x16_bf16 v[134:149], v[158:161], v[14:17], v[134:149]
	ds_read_b128 v[158:161], v212 offset:23264
	ds_read_b128 v[178:181], v213 offset:5120
	s_waitcnt lgkmcnt(7)
	v_mfma_f32_32x32x16_bf16 v[134:149], v[162:165], v[18:21], v[134:149]
	ds_read_b128 v[162:165], v212 offset:23296
	ds_read_b128 v[182:185], v213 offset:7680
	s_waitcnt lgkmcnt(8)
	v_mfma_f32_32x32x16_bf16 v[134:149], v[166:169], v[22:25], v[134:149]
	ds_read_b128 v[166:169], v212 offset:23328
	v_exp_f32_e32 v118, v118
	v_exp_f32_e32 v119, v119
	v_add_f32_e32 v0, v0, v118
	s_waitcnt lgkmcnt(8)
	v_mfma_f32_32x32x16_bf16 v[134:149], v[150:153], v[26:29], v[134:149]
	ds_read_b128 v[150:153], v212 offset:23360
	v_add_f32_e32 v0, v0, v119
	v_exp_f32_e32 v120, v120
	v_exp_f32_e32 v121, v121
	s_waitcnt lgkmcnt(7)
	v_mfma_f32_32x32x16_bf16 v[134:149], v[154:157], v[30:33], v[134:149]
	ds_read_b128 v[154:157], v212 offset:23392
	s_waitcnt vmcnt(9)
	ds_write_b128 v244, v[188:191] offset:46080
	global_load_dwordx4 v[188:191], v248, s[56:57]
	v_add_f32_e32 v0, v0, v120
	v_add_f32_e32 v0, v0, v121
	v_exp_f32_e32 v122, v122
	s_waitcnt lgkmcnt(7)
	v_mfma_f32_32x32x16_bf16 v[134:149], v[158:161], v[34:37], v[134:149]
	s_waitcnt vmcnt(9)
	ds_write_b128 v245, v[192:195] offset:46080
	global_load_dwordx4 v[192:195], v248, s[98:99] offset:-4096
	v_exp_f32_e32 v123, v123
	v_add_f32_e32 v0, v0, v122
	v_add_f32_e32 v0, v0, v123
	s_waitcnt lgkmcnt(6)
	v_mfma_f32_32x32x16_bf16 v[134:149], v[162:165], v[38:41], v[134:149]
	s_waitcnt vmcnt(9)
	ds_write_b128 v246, v[196:199] offset:46080
	global_load_dwordx4 v[196:199], v248, s[98:99]
	v_exp_f32_e32 v124, v124
	v_exp_f32_e32 v125, v125
	v_add_f32_e32 v0, v0, v124
	v_add_f32_e32 v0, v0, v125
	s_waitcnt lgkmcnt(5)
	v_mfma_f32_32x32x16_bf16 v[134:149], v[166:169], v[42:45], v[134:149]
	s_waitcnt vmcnt(9)
	ds_write_b128 v247, v[200:203] offset:46080
	global_load_dwordx4 v[200:203], v235, s[52:53]
	v_cvt_pk_bf16_f32 v118, v118, v119
	v_cvt_pk_bf16_f32 v119, v120, v121
	v_cvt_pk_bf16_f32 v120, v122, v123
	v_cvt_pk_bf16_f32 v121, v124, v125
	s_waitcnt lgkmcnt(5)
	v_mfma_f32_32x32x16_bf16 v[134:149], v[150:153], v[46:49], v[134:149]
	s_waitcnt vmcnt(9)
	ds_write_b128 v247, v[204:207] offset:51200
	global_load_dwordx4 v[204:207], v235, s[100:101]
	v_exp_f32_e32 v126, v126
	v_exp_f32_e32 v127, v127
	v_add_f32_e32 v0, v0, v126
	v_add_f32_e32 v0, v0, v127
	s_waitcnt lgkmcnt(5)
	v_mfma_f32_32x32x16_bf16 v[134:149], v[154:157], v[50:53], v[134:149]
	v_exp_f32_e32 v128, v128
	v_exp_f32_e32 v129, v129
	v_add_f32_e32 v0, v0, v128
	v_add_f32_e32 v0, v0, v129
	v_mfma_f32_32x32x16_bf16 v[54:69], v[170:173], v[118:121], v[54:69]
	ds_read_b128 v[170:173], v213 offset:32
	v_exp_f32_e32 v130, v130
	v_exp_f32_e32 v131, v131
	v_add_f32_e32 v0, v0, v130
	v_mfma_f32_32x32x16_bf16 v[70:85], v[174:177], v[118:121], v[70:85]
	ds_read_b128 v[174:177], v213 offset:2592
	v_add_f32_e32 v0, v0, v131
	v_exp_f32_e32 v132, v132
	v_exp_f32_e32 v133, v133
	v_mfma_f32_32x32x16_bf16 v[86:101], v[178:181], v[118:121], v[86:101]
	ds_read_b128 v[178:181], v213 offset:5152
	v_add_f32_e32 v0, v0, v132
	v_add_f32_e32 v0, v0, v133
	v_cvt_pk_bf16_f32 v126, v126, v127
	v_mfma_f32_32x32x16_bf16 v[102:117], v[182:185], v[118:121], v[102:117]
	ds_read_b128 v[182:185], v213 offset:7712
	v_cvt_pk_bf16_f32 v127, v128, v129
	v_cvt_pk_bf16_f32 v128, v130, v131
	v_cvt_pk_bf16_f32 v129, v132, v133
	s_waitcnt lgkmcnt(3)
	s_nop 1
	v_mfma_f32_32x32x16_bf16 v[54:69], v[170:173], v[126:129], v[54:69]
	s_add_u32 s56, s56, 0x3000
	s_addc_u32 s57, s57, 0
	s_waitcnt lgkmcnt(2)
	v_mfma_f32_32x32x16_bf16 v[70:85], v[174:177], v[126:129], v[70:85]
	s_add_u32 s98, s98, 0x3000
	s_addc_u32 s99, s99, 0
	s_waitcnt lgkmcnt(1)
	v_mfma_f32_32x32x16_bf16 v[86:101], v[178:181], v[126:129], v[86:101]
	s_add_u32 s52, s52, 64
	s_addc_u32 s53, s53, 0
	s_waitcnt lgkmcnt(0)
	v_mfma_f32_32x32x16_bf16 v[102:117], v[182:185], v[126:129], v[102:117]
	s_add_u32 s100, s100, 64
	s_addc_u32 s101, s101, 0
	s_waitcnt lgkmcnt(0)
	s_barrier
	ds_read_b128 v[150:153], v212 offset:46080
	ds_read_b128 v[154:157], v212 offset:46112
	ds_read_b128 v[158:161], v212 offset:46144
	ds_read_b128 v[162:165], v212 offset:46176
	ds_read_b128 v[166:169], v212 offset:46208
	s_waitcnt lgkmcnt(4)
	v_mfma_f32_32x32x16_bf16 v[118:133], v[150:153], v[6:9], 0
	ds_read_b128 v[150:153], v212 offset:46240
	ds_read_b128 v[170:173], v213 offset:23040
	s_waitcnt lgkmcnt(5)
	v_mfma_f32_32x32x16_bf16 v[118:133], v[154:157], v[10:13], v[118:133]
	ds_read_b128 v[154:157], v212 offset:46272
	ds_read_b128 v[174:177], v213 offset:25600
	s_waitcnt lgkmcnt(6)
	v_mfma_f32_32x32x16_bf16 v[118:133], v[158:161], v[14:17], v[118:133]
	ds_read_b128 v[158:161], v212 offset:46304
	ds_read_b128 v[178:181], v213 offset:28160
	s_waitcnt lgkmcnt(7)
	v_mfma_f32_32x32x16_bf16 v[118:133], v[162:165], v[18:21], v[118:133]
	ds_read_b128 v[162:165], v212 offset:46336
	ds_read_b128 v[182:185], v213 offset:30720
	s_waitcnt lgkmcnt(8)
	v_mfma_f32_32x32x16_bf16 v[118:133], v[166:169], v[22:25], v[118:133]
	ds_read_b128 v[166:169], v212 offset:46368
	v_exp_f32_e32 v134, v134
	v_exp_f32_e32 v135, v135
	v_add_f32_e32 v0, v0, v134
	s_waitcnt lgkmcnt(8)
	v_mfma_f32_32x32x16_bf16 v[118:133], v[150:153], v[26:29], v[118:133]
	ds_read_b128 v[150:153], v212 offset:46400
	v_add_f32_e32 v0, v0, v135
	v_exp_f32_e32 v136, v136
	v_exp_f32_e32 v137, v137
	s_waitcnt lgkmcnt(7)
	v_mfma_f32_32x32x16_bf16 v[118:133], v[154:157], v[30:33], v[118:133]
	ds_read_b128 v[154:157], v212 offset:46432
	s_waitcnt vmcnt(9)
	ds_write_b128 v244, v[208:211] offset:0
	global_load_dwordx4 v[208:211], v248, s[56:57]
	v_add_f32_e32 v0, v0, v136
	v_add_f32_e32 v0, v0, v137
	v_exp_f32_e32 v138, v138
	s_waitcnt lgkmcnt(7)
	v_mfma_f32_32x32x16_bf16 v[118:133], v[158:161], v[34:37], v[118:133]
	s_waitcnt vmcnt(9)
	ds_write_b128 v245, v[216:219] offset:0
	global_load_dwordx4 v[216:219], v248, s[98:99] offset:-4096
	v_exp_f32_e32 v139, v139
	v_add_f32_e32 v0, v0, v138
	v_add_f32_e32 v0, v0, v139
	s_waitcnt lgkmcnt(6)
	v_mfma_f32_32x32x16_bf16 v[118:133], v[162:165], v[38:41], v[118:133]
	s_waitcnt vmcnt(9)
	ds_write_b128 v246, v[220:223] offset:0
	global_load_dwordx4 v[220:223], v248, s[98:99]
	v_exp_f32_e32 v140, v140
	v_exp_f32_e32 v141, v141
	v_add_f32_e32 v0, v0, v140
	v_add_f32_e32 v0, v0, v141
	s_waitcnt lgkmcnt(5)
	v_mfma_f32_32x32x16_bf16 v[118:133], v[166:169], v[42:45], v[118:133]
	s_waitcnt vmcnt(9)
	ds_write_b128 v247, v[236:239] offset:0
	global_load_dwordx4 v[236:239], v235, s[52:53]
	v_cvt_pk_bf16_f32 v134, v134, v135
	v_cvt_pk_bf16_f32 v135, v136, v137
	v_cvt_pk_bf16_f32 v136, v138, v139
	v_cvt_pk_bf16_f32 v137, v140, v141
	s_waitcnt lgkmcnt(5)
	v_mfma_f32_32x32x16_bf16 v[118:133], v[150:153], v[46:49], v[118:133]
	s_waitcnt vmcnt(9)
	ds_write_b128 v247, v[240:243] offset:5120
	global_load_dwordx4 v[240:243], v235, s[100:101]
	v_exp_f32_e32 v142, v142
	v_exp_f32_e32 v143, v143
	v_add_f32_e32 v0, v0, v142
	v_add_f32_e32 v0, v0, v143
	s_waitcnt lgkmcnt(5)
	v_mfma_f32_32x32x16_bf16 v[118:133], v[154:157], v[50:53], v[118:133]
	v_exp_f32_e32 v144, v144
	v_exp_f32_e32 v145, v145
	v_add_f32_e32 v0, v0, v144
	v_add_f32_e32 v0, v0, v145
	v_mfma_f32_32x32x16_bf16 v[54:69], v[170:173], v[134:137], v[54:69]
	ds_read_b128 v[170:173], v213 offset:23072
	v_exp_f32_e32 v146, v146
	v_exp_f32_e32 v147, v147
	v_add_f32_e32 v0, v0, v146
	v_mfma_f32_32x32x16_bf16 v[70:85], v[174:177], v[134:137], v[70:85]
	ds_read_b128 v[174:177], v213 offset:25632
	v_add_f32_e32 v0, v0, v147
	v_exp_f32_e32 v148, v148
	v_exp_f32_e32 v149, v149
	v_mfma_f32_32x32x16_bf16 v[86:101], v[178:181], v[134:137], v[86:101]
	ds_read_b128 v[178:181], v213 offset:28192
	v_add_f32_e32 v0, v0, v148
	v_add_f32_e32 v0, v0, v149
	v_cvt_pk_bf16_f32 v142, v142, v143
	v_mfma_f32_32x32x16_bf16 v[102:117], v[182:185], v[134:137], v[102:117]
	ds_read_b128 v[182:185], v213 offset:30752
	v_cvt_pk_bf16_f32 v143, v144, v145
	v_cvt_pk_bf16_f32 v144, v146, v147
	v_cvt_pk_bf16_f32 v145, v148, v149
	s_waitcnt lgkmcnt(3)
	s_nop 1
	v_mfma_f32_32x32x16_bf16 v[54:69], v[170:173], v[142:145], v[54:69]
	s_add_u32 s56, s56, 0x3000
	s_addc_u32 s57, s57, 0
	s_waitcnt lgkmcnt(2)
	v_mfma_f32_32x32x16_bf16 v[70:85], v[174:177], v[142:145], v[70:85]
	s_add_u32 s98, s98, 0x3000
	s_addc_u32 s99, s99, 0
	s_waitcnt lgkmcnt(1)
	v_mfma_f32_32x32x16_bf16 v[86:101], v[178:181], v[142:145], v[86:101]
	s_add_u32 s52, s52, 64
	s_addc_u32 s53, s53, 0
	s_waitcnt lgkmcnt(0)
	v_mfma_f32_32x32x16_bf16 v[102:117], v[182:185], v[142:145], v[102:117]
	s_add_u32 s100, s100, 64
	s_addc_u32 s101, s101, 0
	s_waitcnt lgkmcnt(0)
	s_barrier
	ds_read_b128 v[150:153], v212 offset:0
	ds_read_b128 v[154:157], v212 offset:32
	ds_read_b128 v[158:161], v212 offset:64
	ds_read_b128 v[162:165], v212 offset:96
	ds_read_b128 v[166:169], v212 offset:128
	s_waitcnt lgkmcnt(4)
	v_mfma_f32_32x32x16_bf16 v[134:149], v[150:153], v[6:9], 0
	ds_read_b128 v[150:153], v212 offset:160
	ds_read_b128 v[170:173], v213 offset:46080
	s_waitcnt lgkmcnt(5)
	v_mfma_f32_32x32x16_bf16 v[134:149], v[154:157], v[10:13], v[134:149]
	ds_read_b128 v[154:157], v212 offset:192
	ds_read_b128 v[174:177], v213 offset:48640
	s_waitcnt lgkmcnt(6)
	v_mfma_f32_32x32x16_bf16 v[134:149], v[158:161], v[14:17], v[134:149]
	ds_read_b128 v[158:161], v212 offset:224
	ds_read_b128 v[178:181], v213 offset:51200
	s_waitcnt lgkmcnt(7)
	v_mfma_f32_32x32x16_bf16 v[134:149], v[162:165], v[18:21], v[134:149]
	ds_read_b128 v[162:165], v212 offset:256
	ds_read_b128 v[182:185], v213 offset:53760
	s_waitcnt lgkmcnt(8)
	v_mfma_f32_32x32x16_bf16 v[134:149], v[166:169], v[22:25], v[134:149]
	ds_read_b128 v[166:169], v212 offset:288
	v_exp_f32_e32 v118, v118
	v_exp_f32_e32 v119, v119
	v_add_f32_e32 v0, v0, v118
	s_waitcnt lgkmcnt(8)
	v_mfma_f32_32x32x16_bf16 v[134:149], v[150:153], v[26:29], v[134:149]
	ds_read_b128 v[150:153], v212 offset:320
	v_add_f32_e32 v0, v0, v119
	v_exp_f32_e32 v120, v120
	v_exp_f32_e32 v121, v121
	s_waitcnt lgkmcnt(7)
	v_mfma_f32_32x32x16_bf16 v[134:149], v[154:157], v[30:33], v[134:149]
	ds_read_b128 v[154:157], v212 offset:352
	s_waitcnt vmcnt(9)
	ds_write_b128 v244, v[188:191] offset:23040
	global_load_dwordx4 v[188:191], v248, s[56:57]
	v_add_f32_e32 v0, v0, v120
	v_add_f32_e32 v0, v0, v121
	v_exp_f32_e32 v122, v122
	s_waitcnt lgkmcnt(7)
	v_mfma_f32_32x32x16_bf16 v[134:149], v[158:161], v[34:37], v[134:149]
	s_waitcnt vmcnt(9)
	ds_write_b128 v245, v[192:195] offset:23040
	global_load_dwordx4 v[192:195], v248, s[98:99] offset:-4096
	v_exp_f32_e32 v123, v123
	v_add_f32_e32 v0, v0, v122
	v_add_f32_e32 v0, v0, v123
	s_waitcnt lgkmcnt(6)
	v_mfma_f32_32x32x16_bf16 v[134:149], v[162:165], v[38:41], v[134:149]
	s_waitcnt vmcnt(9)
	ds_write_b128 v246, v[196:199] offset:23040
	global_load_dwordx4 v[196:199], v248, s[98:99]
	v_exp_f32_e32 v124, v124
	v_exp_f32_e32 v125, v125
	v_add_f32_e32 v0, v0, v124
	v_add_f32_e32 v0, v0, v125
	s_waitcnt lgkmcnt(5)
	v_mfma_f32_32x32x16_bf16 v[134:149], v[166:169], v[42:45], v[134:149]
	s_waitcnt vmcnt(9)
	ds_write_b128 v247, v[200:203] offset:23040
	global_load_dwordx4 v[200:203], v235, s[52:53]
	v_cvt_pk_bf16_f32 v118, v118, v119
	v_cvt_pk_bf16_f32 v119, v120, v121
	v_cvt_pk_bf16_f32 v120, v122, v123
	v_cvt_pk_bf16_f32 v121, v124, v125
	s_waitcnt lgkmcnt(5)
	v_mfma_f32_32x32x16_bf16 v[134:149], v[150:153], v[46:49], v[134:149]
	s_waitcnt vmcnt(9)
	ds_write_b128 v247, v[204:207] offset:28160
	global_load_dwordx4 v[204:207], v235, s[100:101]
	v_exp_f32_e32 v126, v126
	v_exp_f32_e32 v127, v127
	v_add_f32_e32 v0, v0, v126
	v_add_f32_e32 v0, v0, v127
	s_waitcnt lgkmcnt(5)
	v_mfma_f32_32x32x16_bf16 v[134:149], v[154:157], v[50:53], v[134:149]
	v_exp_f32_e32 v128, v128
	v_exp_f32_e32 v129, v129
	v_add_f32_e32 v0, v0, v128
	v_add_f32_e32 v0, v0, v129
	v_mfma_f32_32x32x16_bf16 v[54:69], v[170:173], v[118:121], v[54:69]
	ds_read_b128 v[170:173], v213 offset:46112
	v_exp_f32_e32 v130, v130
	v_exp_f32_e32 v131, v131
	v_add_f32_e32 v0, v0, v130
	v_mfma_f32_32x32x16_bf16 v[70:85], v[174:177], v[118:121], v[70:85]
	ds_read_b128 v[174:177], v213 offset:48672
	v_add_f32_e32 v0, v0, v131
	v_exp_f32_e32 v132, v132
	v_exp_f32_e32 v133, v133
	v_mfma_f32_32x32x16_bf16 v[86:101], v[178:181], v[118:121], v[86:101]
	ds_read_b128 v[178:181], v213 offset:51232
	v_add_f32_e32 v0, v0, v132
	v_add_f32_e32 v0, v0, v133
	v_cvt_pk_bf16_f32 v126, v126, v127
	v_mfma_f32_32x32x16_bf16 v[102:117], v[182:185], v[118:121], v[102:117]
	ds_read_b128 v[182:185], v213 offset:53792
	v_cvt_pk_bf16_f32 v127, v128, v129
	v_cvt_pk_bf16_f32 v128, v130, v131
	v_cvt_pk_bf16_f32 v129, v132, v133
	s_waitcnt lgkmcnt(3)
	s_nop 1
	v_mfma_f32_32x32x16_bf16 v[54:69], v[170:173], v[126:129], v[54:69]
	s_add_u32 s56, s56, 0x3000
	s_addc_u32 s57, s57, 0
	s_waitcnt lgkmcnt(2)
	v_mfma_f32_32x32x16_bf16 v[70:85], v[174:177], v[126:129], v[70:85]
	s_add_u32 s98, s98, 0x3000
	s_addc_u32 s99, s99, 0
	s_waitcnt lgkmcnt(1)
	v_mfma_f32_32x32x16_bf16 v[86:101], v[178:181], v[126:129], v[86:101]
	s_add_u32 s52, s52, 64
	s_addc_u32 s53, s53, 0
	s_waitcnt lgkmcnt(0)
	v_mfma_f32_32x32x16_bf16 v[102:117], v[182:185], v[126:129], v[102:117]
	s_add_u32 s100, s100, 64
	s_addc_u32 s101, s101, 0
	s_waitcnt lgkmcnt(0)
	s_barrier
	ds_read_b128 v[150:153], v212 offset:23040
	ds_read_b128 v[154:157], v212 offset:23072
	ds_read_b128 v[158:161], v212 offset:23104
	ds_read_b128 v[162:165], v212 offset:23136
	ds_read_b128 v[166:169], v212 offset:23168
	s_waitcnt lgkmcnt(4)
	v_mfma_f32_32x32x16_bf16 v[118:133], v[150:153], v[6:9], 0
	ds_read_b128 v[150:153], v212 offset:23200
	ds_read_b128 v[170:173], v213 offset:0
	s_waitcnt lgkmcnt(5)
	v_mfma_f32_32x32x16_bf16 v[118:133], v[154:157], v[10:13], v[118:133]
	ds_read_b128 v[154:157], v212 offset:23232
	ds_read_b128 v[174:177], v213 offset:2560
	s_waitcnt lgkmcnt(6)
	v_mfma_f32_32x32x16_bf16 v[118:133], v[158:161], v[14:17], v[118:133]
	ds_read_b128 v[158:161], v212 offset:23264
	ds_read_b128 v[178:181], v213 offset:5120
	s_waitcnt lgkmcnt(7)
	v_mfma_f32_32x32x16_bf16 v[118:133], v[162:165], v[18:21], v[118:133]
	ds_read_b128 v[162:165], v212 offset:23296
	ds_read_b128 v[182:185], v213 offset:7680
	s_waitcnt lgkmcnt(8)
	v_mfma_f32_32x32x16_bf16 v[118:133], v[166:169], v[22:25], v[118:133]
	ds_read_b128 v[166:169], v212 offset:23328
	v_exp_f32_e32 v134, v134
	v_exp_f32_e32 v135, v135
	v_add_f32_e32 v0, v0, v134
	s_waitcnt lgkmcnt(8)
	v_mfma_f32_32x32x16_bf16 v[118:133], v[150:153], v[26:29], v[118:133]
	ds_read_b128 v[150:153], v212 offset:23360
	v_add_f32_e32 v0, v0, v135
	v_exp_f32_e32 v136, v136
	v_exp_f32_e32 v137, v137
	s_waitcnt lgkmcnt(7)
	v_mfma_f32_32x32x16_bf16 v[118:133], v[154:157], v[30:33], v[118:133]
	ds_read_b128 v[154:157], v212 offset:23392
	s_waitcnt vmcnt(9)
	ds_write_b128 v244, v[208:211] offset:46080
	global_load_dwordx4 v[208:211], v248, s[56:57]
	v_add_f32_e32 v0, v0, v136
	v_add_f32_e32 v0, v0, v137
	v_exp_f32_e32 v138, v138
	s_waitcnt lgkmcnt(7)
	v_mfma_f32_32x32x16_bf16 v[118:133], v[158:161], v[34:37], v[118:133]
	s_waitcnt vmcnt(9)
	ds_write_b128 v245, v[216:219] offset:46080
	global_load_dwordx4 v[216:219], v248, s[98:99] offset:-4096
	v_exp_f32_e32 v139, v139
	v_add_f32_e32 v0, v0, v138
	v_add_f32_e32 v0, v0, v139
	s_waitcnt lgkmcnt(6)
	v_mfma_f32_32x32x16_bf16 v[118:133], v[162:165], v[38:41], v[118:133]
	s_waitcnt vmcnt(9)
	ds_write_b128 v246, v[220:223] offset:46080
	global_load_dwordx4 v[220:223], v248, s[98:99]
	v_exp_f32_e32 v140, v140
	v_exp_f32_e32 v141, v141
	v_add_f32_e32 v0, v0, v140
	v_add_f32_e32 v0, v0, v141
	s_waitcnt lgkmcnt(5)
	v_mfma_f32_32x32x16_bf16 v[118:133], v[166:169], v[42:45], v[118:133]
	s_waitcnt vmcnt(9)
	ds_write_b128 v247, v[236:239] offset:46080
	global_load_dwordx4 v[236:239], v235, s[52:53]
	v_cvt_pk_bf16_f32 v134, v134, v135
	v_cvt_pk_bf16_f32 v135, v136, v137
	v_cvt_pk_bf16_f32 v136, v138, v139
	v_cvt_pk_bf16_f32 v137, v140, v141
	s_waitcnt lgkmcnt(5)
	v_mfma_f32_32x32x16_bf16 v[118:133], v[150:153], v[46:49], v[118:133]
	s_waitcnt vmcnt(9)
	ds_write_b128 v247, v[240:243] offset:51200
	global_load_dwordx4 v[240:243], v235, s[100:101]
	v_exp_f32_e32 v142, v142
	v_exp_f32_e32 v143, v143
	v_add_f32_e32 v0, v0, v142
	v_add_f32_e32 v0, v0, v143
	s_waitcnt lgkmcnt(5)
	v_mfma_f32_32x32x16_bf16 v[118:133], v[154:157], v[50:53], v[118:133]
	v_exp_f32_e32 v144, v144
	v_exp_f32_e32 v145, v145
	v_add_f32_e32 v0, v0, v144
	v_add_f32_e32 v0, v0, v145
	v_mfma_f32_32x32x16_bf16 v[54:69], v[170:173], v[134:137], v[54:69]
	ds_read_b128 v[170:173], v213 offset:32
	v_exp_f32_e32 v146, v146
	v_exp_f32_e32 v147, v147
	v_add_f32_e32 v0, v0, v146
	v_mfma_f32_32x32x16_bf16 v[70:85], v[174:177], v[134:137], v[70:85]
	ds_read_b128 v[174:177], v213 offset:2592
	v_add_f32_e32 v0, v0, v147
	v_exp_f32_e32 v148, v148
	v_exp_f32_e32 v149, v149
	v_mfma_f32_32x32x16_bf16 v[86:101], v[178:181], v[134:137], v[86:101]
	ds_read_b128 v[178:181], v213 offset:5152
	v_add_f32_e32 v0, v0, v148
	v_add_f32_e32 v0, v0, v149
	v_cvt_pk_bf16_f32 v142, v142, v143
	v_mfma_f32_32x32x16_bf16 v[102:117], v[182:185], v[134:137], v[102:117]
	ds_read_b128 v[182:185], v213 offset:7712
	v_cvt_pk_bf16_f32 v143, v144, v145
	v_cvt_pk_bf16_f32 v144, v146, v147
	v_cvt_pk_bf16_f32 v145, v148, v149
	s_waitcnt lgkmcnt(3)
	s_nop 1
	v_mfma_f32_32x32x16_bf16 v[54:69], v[170:173], v[142:145], v[54:69]
	s_add_u32 s56, s56, 0x3000
	s_addc_u32 s57, s57, 0
	s_waitcnt lgkmcnt(2)
	v_mfma_f32_32x32x16_bf16 v[70:85], v[174:177], v[142:145], v[70:85]
	s_add_u32 s98, s98, 0x3000
	s_addc_u32 s99, s99, 0
	s_waitcnt lgkmcnt(1)
	v_mfma_f32_32x32x16_bf16 v[86:101], v[178:181], v[142:145], v[86:101]
	s_add_u32 s52, s52, 64
	s_addc_u32 s53, s53, 0
	s_waitcnt lgkmcnt(0)
	v_mfma_f32_32x32x16_bf16 v[102:117], v[182:185], v[142:145], v[102:117]
	s_add_u32 s100, s100, 64
	s_addc_u32 s101, s101, 0
	s_waitcnt lgkmcnt(0)
	s_barrier
	ds_read_b128 v[150:153], v212 offset:46080
	ds_read_b128 v[154:157], v212 offset:46112
	ds_read_b128 v[158:161], v212 offset:46144
	ds_read_b128 v[162:165], v212 offset:46176
	ds_read_b128 v[166:169], v212 offset:46208
	s_waitcnt lgkmcnt(4)
	v_mfma_f32_32x32x16_bf16 v[134:149], v[150:153], v[6:9], 0
	ds_read_b128 v[150:153], v212 offset:46240
	ds_read_b128 v[170:173], v213 offset:23040
	s_waitcnt lgkmcnt(5)
	v_mfma_f32_32x32x16_bf16 v[134:149], v[154:157], v[10:13], v[134:149]
	ds_read_b128 v[154:157], v212 offset:46272
	ds_read_b128 v[174:177], v213 offset:25600
	s_waitcnt lgkmcnt(6)
	v_mfma_f32_32x32x16_bf16 v[134:149], v[158:161], v[14:17], v[134:149]
	ds_read_b128 v[158:161], v212 offset:46304
	ds_read_b128 v[178:181], v213 offset:28160
	s_waitcnt lgkmcnt(7)
	v_mfma_f32_32x32x16_bf16 v[134:149], v[162:165], v[18:21], v[134:149]
	ds_read_b128 v[162:165], v212 offset:46336
	ds_read_b128 v[182:185], v213 offset:30720
	s_waitcnt lgkmcnt(8)
	v_mfma_f32_32x32x16_bf16 v[134:149], v[166:169], v[22:25], v[134:149]
	ds_read_b128 v[166:169], v212 offset:46368
	v_exp_f32_e32 v118, v118
	v_exp_f32_e32 v119, v119
	v_add_f32_e32 v0, v0, v118
	s_waitcnt lgkmcnt(8)
	v_mfma_f32_32x32x16_bf16 v[134:149], v[150:153], v[26:29], v[134:149]
	ds_read_b128 v[150:153], v212 offset:46400
	v_add_f32_e32 v0, v0, v119
	v_exp_f32_e32 v120, v120
	v_exp_f32_e32 v121, v121
	s_waitcnt lgkmcnt(7)
	v_mfma_f32_32x32x16_bf16 v[134:149], v[154:157], v[30:33], v[134:149]
	ds_read_b128 v[154:157], v212 offset:46432
	s_waitcnt vmcnt(9)
	ds_write_b128 v244, v[188:191] offset:0
	global_load_dwordx4 v[188:191], v248, s[56:57]
	v_add_f32_e32 v0, v0, v120
	v_add_f32_e32 v0, v0, v121
	v_exp_f32_e32 v122, v122
	s_waitcnt lgkmcnt(7)
	v_mfma_f32_32x32x16_bf16 v[134:149], v[158:161], v[34:37], v[134:149]
	s_waitcnt vmcnt(9)
	ds_write_b128 v245, v[192:195] offset:0
	global_load_dwordx4 v[192:195], v248, s[98:99] offset:-4096
	v_exp_f32_e32 v123, v123
	v_add_f32_e32 v0, v0, v122
	v_add_f32_e32 v0, v0, v123
	s_waitcnt lgkmcnt(6)
	v_mfma_f32_32x32x16_bf16 v[134:149], v[162:165], v[38:41], v[134:149]
	s_waitcnt vmcnt(9)
	ds_write_b128 v246, v[196:199] offset:0
	global_load_dwordx4 v[196:199], v248, s[98:99]
	v_exp_f32_e32 v124, v124
	v_exp_f32_e32 v125, v125
	v_add_f32_e32 v0, v0, v124
	v_add_f32_e32 v0, v0, v125
	s_waitcnt lgkmcnt(5)
	v_mfma_f32_32x32x16_bf16 v[134:149], v[166:169], v[42:45], v[134:149]
	s_waitcnt vmcnt(9)
	ds_write_b128 v247, v[200:203] offset:0
	global_load_dwordx4 v[200:203], v235, s[52:53]
	v_cvt_pk_bf16_f32 v118, v118, v119
	v_cvt_pk_bf16_f32 v119, v120, v121
	v_cvt_pk_bf16_f32 v120, v122, v123
	v_cvt_pk_bf16_f32 v121, v124, v125
	s_waitcnt lgkmcnt(5)
	v_mfma_f32_32x32x16_bf16 v[134:149], v[150:153], v[46:49], v[134:149]
	s_waitcnt vmcnt(9)
	ds_write_b128 v247, v[204:207] offset:5120
	global_load_dwordx4 v[204:207], v235, s[100:101]
	v_exp_f32_e32 v126, v126
	v_exp_f32_e32 v127, v127
	v_add_f32_e32 v0, v0, v126
	v_add_f32_e32 v0, v0, v127
	s_waitcnt lgkmcnt(5)
	v_mfma_f32_32x32x16_bf16 v[134:149], v[154:157], v[50:53], v[134:149]
	v_exp_f32_e32 v128, v128
	v_exp_f32_e32 v129, v129
	v_add_f32_e32 v0, v0, v128
	v_add_f32_e32 v0, v0, v129
	v_mfma_f32_32x32x16_bf16 v[54:69], v[170:173], v[118:121], v[54:69]
	ds_read_b128 v[170:173], v213 offset:23072
	v_exp_f32_e32 v130, v130
	v_exp_f32_e32 v131, v131
	v_add_f32_e32 v0, v0, v130
	v_mfma_f32_32x32x16_bf16 v[70:85], v[174:177], v[118:121], v[70:85]
	ds_read_b128 v[174:177], v213 offset:25632
	v_add_f32_e32 v0, v0, v131
	v_exp_f32_e32 v132, v132
	v_exp_f32_e32 v133, v133
	v_mfma_f32_32x32x16_bf16 v[86:101], v[178:181], v[118:121], v[86:101]
	ds_read_b128 v[178:181], v213 offset:28192
	v_add_f32_e32 v0, v0, v132
	v_add_f32_e32 v0, v0, v133
	v_cvt_pk_bf16_f32 v126, v126, v127
	v_mfma_f32_32x32x16_bf16 v[102:117], v[182:185], v[118:121], v[102:117]
	ds_read_b128 v[182:185], v213 offset:30752
	v_cvt_pk_bf16_f32 v127, v128, v129
	v_cvt_pk_bf16_f32 v128, v130, v131
	v_cvt_pk_bf16_f32 v129, v132, v133
	s_waitcnt lgkmcnt(3)
	s_nop 1
	v_mfma_f32_32x32x16_bf16 v[54:69], v[170:173], v[126:129], v[54:69]
	s_add_u32 s56, s56, 0x3000
	s_addc_u32 s57, s57, 0
	s_waitcnt lgkmcnt(2)
	v_mfma_f32_32x32x16_bf16 v[70:85], v[174:177], v[126:129], v[70:85]
	s_add_u32 s98, s98, 0x3000
	s_addc_u32 s99, s99, 0
	s_waitcnt lgkmcnt(1)
	v_mfma_f32_32x32x16_bf16 v[86:101], v[178:181], v[126:129], v[86:101]
	s_add_u32 s52, s52, 64
	s_addc_u32 s53, s53, 0
	s_waitcnt lgkmcnt(0)
	v_mfma_f32_32x32x16_bf16 v[102:117], v[182:185], v[126:129], v[102:117]
	s_add_u32 s100, s100, 64
	s_addc_u32 s101, s101, 0
	s_waitcnt lgkmcnt(0)
	s_barrier
; __device__ __forceinline__ void attn_item(const Params& p, int b, int h, int qt, float shift, unsigned char* smem) {
;     ...
; #pragma unroll 1
;   for (int tt = 1; tt < ntile - 1; tt += 2) {
;     ATT_STEP(sB, sA, tt);
;     ATT_STEP(sA, sB, tt + 1);
;   }
	ds_read_b128 v[150:153], v212 offset:0
	ds_read_b128 v[154:157], v212 offset:32
	ds_read_b128 v[158:161], v212 offset:64
	ds_read_b128 v[162:165], v212 offset:96
	ds_read_b128 v[166:169], v212 offset:128
	s_waitcnt lgkmcnt(4)
	v_mfma_f32_32x32x16_bf16 v[118:133], v[150:153], v[6:9], 0
	ds_read_b128 v[150:153], v212 offset:160
	ds_read_b128 v[170:173], v213 offset:46080
	s_waitcnt lgkmcnt(5)
	v_mfma_f32_32x32x16_bf16 v[118:133], v[154:157], v[10:13], v[118:133]
	ds_read_b128 v[154:157], v212 offset:192
	ds_read_b128 v[174:177], v213 offset:48640
	s_waitcnt lgkmcnt(6)
	v_mfma_f32_32x32x16_bf16 v[118:133], v[158:161], v[14:17], v[118:133]
	ds_read_b128 v[158:161], v212 offset:224
	ds_read_b128 v[178:181], v213 offset:51200
	s_waitcnt lgkmcnt(7)
	v_mfma_f32_32x32x16_bf16 v[118:133], v[162:165], v[18:21], v[118:133]
	ds_read_b128 v[162:165], v212 offset:256
	ds_read_b128 v[182:185], v213 offset:53760
	s_waitcnt lgkmcnt(8)
	v_mfma_f32_32x32x16_bf16 v[118:133], v[166:169], v[22:25], v[118:133]
	ds_read_b128 v[166:169], v212 offset:288
	v_exp_f32_e32 v134, v134
	v_exp_f32_e32 v135, v135
	v_add_f32_e32 v0, v0, v134
	s_waitcnt lgkmcnt(8)
	v_mfma_f32_32x32x16_bf16 v[118:133], v[150:153], v[26:29], v[118:133]
	ds_read_b128 v[150:153], v212 offset:320
	v_add_f32_e32 v0, v0, v135
	v_exp_f32_e32 v136, v136
	v_exp_f32_e32 v137, v137
	s_waitcnt lgkmcnt(7)
	v_mfma_f32_32x32x16_bf16 v[118:133], v[154:157], v[30:33], v[118:133]
	ds_read_b128 v[154:157], v212 offset:352
	s_waitcnt vmcnt(9)
	ds_write_b128 v244, v[208:211] offset:23040
	global_load_dwordx4 v[208:211], v248, s[56:57]
	v_add_f32_e32 v0, v0, v136
	v_add_f32_e32 v0, v0, v137
	v_exp_f32_e32 v138, v138
	s_waitcnt lgkmcnt(7)
	v_mfma_f32_32x32x16_bf16 v[118:133], v[158:161], v[34:37], v[118:133]
	s_waitcnt vmcnt(9)
	ds_write_b128 v245, v[216:219] offset:23040
	global_load_dwordx4 v[216:219], v248, s[98:99] offset:-4096
	v_exp_f32_e32 v139, v139
	v_add_f32_e32 v0, v0, v138
	v_add_f32_e32 v0, v0, v139
	s_waitcnt lgkmcnt(6)
	v_mfma_f32_32x32x16_bf16 v[118:133], v[162:165], v[38:41], v[118:133]
	s_waitcnt vmcnt(9)
	ds_write_b128 v246, v[220:223] offset:23040
	global_load_dwordx4 v[220:223], v248, s[98:99]
	v_exp_f32_e32 v140, v140
	v_exp_f32_e32 v141, v141
	v_add_f32_e32 v0, v0, v140
	v_add_f32_e32 v0, v0, v141
	s_waitcnt lgkmcnt(5)
	v_mfma_f32_32x32x16_bf16 v[118:133], v[166:169], v[42:45], v[118:133]
	s_waitcnt vmcnt(9)
	ds_write_b128 v247, v[236:239] offset:23040
	global_load_dwordx4 v[236:239], v235, s[52:53]
	v_cvt_pk_bf16_f32 v134, v134, v135
	v_cvt_pk_bf16_f32 v135, v136, v137
	v_cvt_pk_bf16_f32 v136, v138, v139
	v_cvt_pk_bf16_f32 v137, v140, v141
	s_waitcnt lgkmcnt(5)
	v_mfma_f32_32x32x16_bf16 v[118:133], v[150:153], v[46:49], v[118:133]
	s_waitcnt vmcnt(9)
	ds_write_b128 v247, v[240:243] offset:28160
	global_load_dwordx4 v[240:243], v235, s[100:101]
	v_exp_f32_e32 v142, v142
	v_exp_f32_e32 v143, v143
	v_add_f32_e32 v0, v0, v142
	v_add_f32_e32 v0, v0, v143
	s_waitcnt lgkmcnt(5)
	v_mfma_f32_32x32x16_bf16 v[118:133], v[154:157], v[50:53], v[118:133]
	v_exp_f32_e32 v144, v144
	v_exp_f32_e32 v145, v145
	v_add_f32_e32 v0, v0, v144
	v_add_f32_e32 v0, v0, v145
	v_mfma_f32_32x32x16_bf16 v[54:69], v[170:173], v[134:137], v[54:69]
	ds_read_b128 v[170:173], v213 offset:46112
	v_exp_f32_e32 v146, v146
	v_exp_f32_e32 v147, v147
	v_add_f32_e32 v0, v0, v146
	v_mfma_f32_32x32x16_bf16 v[70:85], v[174:177], v[134:137], v[70:85]
	ds_read_b128 v[174:177], v213 offset:48672
	v_add_f32_e32 v0, v0, v147
	v_exp_f32_e32 v148, v148
	v_exp_f32_e32 v149, v149
	v_mfma_f32_32x32x16_bf16 v[86:101], v[178:181], v[134:137], v[86:101]
	ds_read_b128 v[178:181], v213 offset:51232
	v_add_f32_e32 v0, v0, v148
	v_add_f32_e32 v0, v0, v149
	v_cvt_pk_bf16_f32 v142, v142, v143
	v_mfma_f32_32x32x16_bf16 v[102:117], v[182:185], v[134:137], v[102:117]
	ds_read_b128 v[182:185], v213 offset:53792
	v_cvt_pk_bf16_f32 v143, v144, v145
	v_cvt_pk_bf16_f32 v144, v146, v147
	v_cvt_pk_bf16_f32 v145, v148, v149
	s_waitcnt lgkmcnt(3)
	s_nop 1
	v_mfma_f32_32x32x16_bf16 v[54:69], v[170:173], v[142:145], v[54:69]
	s_add_u32 s56, s56, 0x3000
	s_addc_u32 s57, s57, 0
	s_waitcnt lgkmcnt(2)
	v_mfma_f32_32x32x16_bf16 v[70:85], v[174:177], v[142:145], v[70:85]
	s_add_u32 s98, s98, 0x3000
	s_addc_u32 s99, s99, 0
	s_waitcnt lgkmcnt(1)
	v_mfma_f32_32x32x16_bf16 v[86:101], v[178:181], v[142:145], v[86:101]
	s_add_u32 s52, s52, 64
	s_addc_u32 s53, s53, 0
	s_waitcnt lgkmcnt(0)
	v_mfma_f32_32x32x16_bf16 v[102:117], v[182:185], v[142:145], v[102:117]
	s_add_u32 s100, s100, 64
	s_addc_u32 s101, s101, 0
	s_waitcnt lgkmcnt(0)
	s_barrier
	s_sub_i32 s47, s47, 1
	s_cmp_lg_u32 s47, 0
	s_cbranch_scc1 .Lfa_loop
; __device__ __forceinline__ void attn_item(const Params& p, int b, int h, int qt, float shift, unsigned char* smem) {
;     ...
;   ATT_STEP(sB, sA, ntile - 1);
	ds_read_b128 v[150:153], v212 offset:23040
	ds_read_b128 v[154:157], v212 offset:23072
	ds_read_b128 v[158:161], v212 offset:23104
	ds_read_b128 v[162:165], v212 offset:23136
	ds_read_b128 v[166:169], v212 offset:23168
	s_waitcnt lgkmcnt(4)
	v_mfma_f32_32x32x16_bf16 v[134:149], v[150:153], v[6:9], 0
	ds_read_b128 v[150:153], v212 offset:23200
	ds_read_b128 v[170:173], v213 offset:0
	s_waitcnt lgkmcnt(5)
	v_mfma_f32_32x32x16_bf16 v[134:149], v[154:157], v[10:13], v[134:149]
	ds_read_b128 v[154:157], v212 offset:23232
	ds_read_b128 v[174:177], v213 offset:2560
	s_waitcnt lgkmcnt(6)
	v_mfma_f32_32x32x16_bf16 v[134:149], v[158:161], v[14:17], v[134:149]
	ds_read_b128 v[158:161], v212 offset:23264
	ds_read_b128 v[178:181], v213 offset:5120
	s_waitcnt lgkmcnt(7)
	v_mfma_f32_32x32x16_bf16 v[134:149], v[162:165], v[18:21], v[134:149]
	ds_read_b128 v[162:165], v212 offset:23296
	ds_read_b128 v[182:185], v213 offset:7680
	s_waitcnt lgkmcnt(8)
	v_mfma_f32_32x32x16_bf16 v[134:149], v[166:169], v[22:25], v[134:149]
	ds_read_b128 v[166:169], v212 offset:23328
	v_exp_f32_e32 v118, v118
	v_exp_f32_e32 v119, v119
	v_add_f32_e32 v0, v0, v118
	s_waitcnt lgkmcnt(8)
	v_mfma_f32_32x32x16_bf16 v[134:149], v[150:153], v[26:29], v[134:149]
	ds_read_b128 v[150:153], v212 offset:23360
	v_add_f32_e32 v0, v0, v119
	v_exp_f32_e32 v120, v120
	v_exp_f32_e32 v121, v121
	s_waitcnt lgkmcnt(7)
	v_mfma_f32_32x32x16_bf16 v[134:149], v[154:157], v[30:33], v[134:149]
	ds_read_b128 v[154:157], v212 offset:23392
	s_waitcnt vmcnt(9)
	ds_write_b128 v244, v[188:191] offset:46080
	global_load_dwordx4 v[188:191], v248, s[56:57]
	v_add_f32_e32 v0, v0, v120
	v_add_f32_e32 v0, v0, v121
	v_exp_f32_e32 v122, v122
	s_waitcnt lgkmcnt(7)
	v_mfma_f32_32x32x16_bf16 v[134:149], v[158:161], v[34:37], v[134:149]
	s_waitcnt vmcnt(9)
	ds_write_b128 v245, v[192:195] offset:46080
	global_load_dwordx4 v[192:195], v248, s[98:99] offset:-4096
	v_exp_f32_e32 v123, v123
	v_add_f32_e32 v0, v0, v122
	v_add_f32_e32 v0, v0, v123
	s_waitcnt lgkmcnt(6)
	v_mfma_f32_32x32x16_bf16 v[134:149], v[162:165], v[38:41], v[134:149]
	s_waitcnt vmcnt(9)
	ds_write_b128 v246, v[196:199] offset:46080
	global_load_dwordx4 v[196:199], v248, s[98:99]
	v_exp_f32_e32 v124, v124
	v_exp_f32_e32 v125, v125
	v_add_f32_e32 v0, v0, v124
	v_add_f32_e32 v0, v0, v125
	s_waitcnt lgkmcnt(5)
	v_mfma_f32_32x32x16_bf16 v[134:149], v[166:169], v[42:45], v[134:149]
	s_waitcnt vmcnt(9)
	ds_write_b128 v247, v[200:203] offset:46080
	global_load_dwordx4 v[200:203], v235, s[52:53]
	v_cvt_pk_bf16_f32 v118, v118, v119
	v_cvt_pk_bf16_f32 v119, v120, v121
	v_cvt_pk_bf16_f32 v120, v122, v123
	v_cvt_pk_bf16_f32 v121, v124, v125
	s_waitcnt lgkmcnt(5)
	v_mfma_f32_32x32x16_bf16 v[134:149], v[150:153], v[46:49], v[134:149]
	s_waitcnt vmcnt(9)
	ds_write_b128 v247, v[204:207] offset:51200
	global_load_dwordx4 v[204:207], v235, s[100:101]
	v_exp_f32_e32 v126, v126
	v_exp_f32_e32 v127, v127
	v_add_f32_e32 v0, v0, v126
	v_add_f32_e32 v0, v0, v127
	s_waitcnt lgkmcnt(5)
	v_mfma_f32_32x32x16_bf16 v[134:149], v[154:157], v[50:53], v[134:149]
	v_exp_f32_e32 v128, v128
	v_exp_f32_e32 v129, v129
	v_add_f32_e32 v0, v0, v128
	v_add_f32_e32 v0, v0, v129
	v_mfma_f32_32x32x16_bf16 v[54:69], v[170:173], v[118:121], v[54:69]
	ds_read_b128 v[170:173], v213 offset:32
	v_exp_f32_e32 v130, v130
	v_exp_f32_e32 v131, v131
	v_add_f32_e32 v0, v0, v130
	v_mfma_f32_32x32x16_bf16 v[70:85], v[174:177], v[118:121], v[70:85]
	ds_read_b128 v[174:177], v213 offset:2592
	v_add_f32_e32 v0, v0, v131
	v_exp_f32_e32 v132, v132
	v_exp_f32_e32 v133, v133
	v_mfma_f32_32x32x16_bf16 v[86:101], v[178:181], v[118:121], v[86:101]
	ds_read_b128 v[178:181], v213 offset:5152
	v_add_f32_e32 v0, v0, v132
	v_add_f32_e32 v0, v0, v133
	v_cvt_pk_bf16_f32 v126, v126, v127
	v_mfma_f32_32x32x16_bf16 v[102:117], v[182:185], v[118:121], v[102:117]
	ds_read_b128 v[182:185], v213 offset:7712
	v_cvt_pk_bf16_f32 v127, v128, v129
	v_cvt_pk_bf16_f32 v128, v130, v131
	v_cvt_pk_bf16_f32 v129, v132, v133
	s_waitcnt lgkmcnt(3)
	s_nop 1
	v_mfma_f32_32x32x16_bf16 v[54:69], v[170:173], v[126:129], v[54:69]
	s_add_u32 s56, s56, 0x3000
	s_addc_u32 s57, s57, 0
	s_waitcnt lgkmcnt(2)
	v_mfma_f32_32x32x16_bf16 v[70:85], v[174:177], v[126:129], v[70:85]
	s_add_u32 s98, s98, 0x3000
	s_addc_u32 s99, s99, 0
	s_waitcnt lgkmcnt(1)
	v_mfma_f32_32x32x16_bf16 v[86:101], v[178:181], v[126:129], v[86:101]
	s_add_u32 s52, s52, 64
	s_addc_u32 s53, s53, 0
	s_waitcnt lgkmcnt(0)
	v_mfma_f32_32x32x16_bf16 v[102:117], v[182:185], v[126:129], v[102:117]
	s_add_u32 s100, s100, 64
	s_addc_u32 s101, s101, 0
	s_waitcnt lgkmcnt(0)
	s_barrier
; __device__ __forceinline__ void attn_item(const Params& p, int b, int h, int qt, float shift, unsigned char* smem) {
;     ...
;   ATT_STEP(sB, sA, ntile - 1);
	ds_read_b128 v[150:153], v212 offset:46080
	ds_read_b128 v[154:157], v212 offset:46112
	ds_read_b128 v[158:161], v212 offset:46144
	ds_read_b128 v[162:165], v212 offset:46176
	ds_read_b128 v[166:169], v212 offset:46208
	s_waitcnt lgkmcnt(4)
	v_mfma_f32_32x32x16_bf16 v[118:133], v[150:153], v[6:9], 0
	ds_read_b128 v[150:153], v212 offset:46240
	ds_read_b128 v[170:173], v213 offset:23040
	s_waitcnt lgkmcnt(5)
	v_mfma_f32_32x32x16_bf16 v[118:133], v[154:157], v[10:13], v[118:133]
	ds_read_b128 v[154:157], v212 offset:46272
	ds_read_b128 v[174:177], v213 offset:25600
	s_waitcnt lgkmcnt(6)
	v_mfma_f32_32x32x16_bf16 v[118:133], v[158:161], v[14:17], v[118:133]
	ds_read_b128 v[158:161], v212 offset:46304
	ds_read_b128 v[178:181], v213 offset:28160
	s_waitcnt lgkmcnt(7)
	v_mfma_f32_32x32x16_bf16 v[118:133], v[162:165], v[18:21], v[118:133]
	ds_read_b128 v[162:165], v212 offset:46336
	ds_read_b128 v[182:185], v213 offset:30720
	s_waitcnt lgkmcnt(8)
	v_mfma_f32_32x32x16_bf16 v[118:133], v[166:169], v[22:25], v[118:133]
	ds_read_b128 v[166:169], v212 offset:46368
	v_exp_f32_e32 v134, v134
	v_exp_f32_e32 v135, v135
	v_add_f32_e32 v0, v0, v134
	s_waitcnt lgkmcnt(8)
	v_mfma_f32_32x32x16_bf16 v[118:133], v[150:153], v[26:29], v[118:133]
	ds_read_b128 v[150:153], v212 offset:46400
	v_add_f32_e32 v0, v0, v135
	v_exp_f32_e32 v136, v136
	v_exp_f32_e32 v137, v137
	s_waitcnt lgkmcnt(7)
	v_mfma_f32_32x32x16_bf16 v[118:133], v[154:157], v[30:33], v[118:133]
	ds_read_b128 v[154:157], v212 offset:46432
	s_waitcnt vmcnt(9)
	ds_write_b128 v244, v[208:211] offset:0
	global_load_dwordx4 v[208:211], v248, s[56:57]
	v_add_f32_e32 v0, v0, v136
	v_add_f32_e32 v0, v0, v137
	v_exp_f32_e32 v138, v138
	s_waitcnt lgkmcnt(7)
	v_mfma_f32_32x32x16_bf16 v[118:133], v[158:161], v[34:37], v[118:133]
	s_waitcnt vmcnt(9)
	ds_write_b128 v245, v[216:219] offset:0
	global_load_dwordx4 v[216:219], v248, s[98:99] offset:-4096
	v_exp_f32_e32 v139, v139
	v_add_f32_e32 v0, v0, v138
	v_add_f32_e32 v0, v0, v139
	s_waitcnt lgkmcnt(6)
	v_mfma_f32_32x32x16_bf16 v[118:133], v[162:165], v[38:41], v[118:133]
	s_waitcnt vmcnt(9)
	ds_write_b128 v246, v[220:223] offset:0
	global_load_dwordx4 v[220:223], v248, s[98:99]
	v_exp_f32_e32 v140, v140
	v_exp_f32_e32 v141, v141
	v_add_f32_e32 v0, v0, v140
	v_add_f32_e32 v0, v0, v141
	s_waitcnt lgkmcnt(5)
	v_mfma_f32_32x32x16_bf16 v[118:133], v[166:169], v[42:45], v[118:133]
	s_waitcnt vmcnt(9)
	ds_write_b128 v247, v[236:239] offset:0
	global_load_dwordx4 v[236:239], v235, s[52:53]
	v_cvt_pk_bf16_f32 v134, v134, v135
	v_cvt_pk_bf16_f32 v135, v136, v137
	v_cvt_pk_bf16_f32 v136, v138, v139
	v_cvt_pk_bf16_f32 v137, v140, v141
	s_waitcnt lgkmcnt(5)
	v_mfma_f32_32x32x16_bf16 v[118:133], v[150:153], v[46:49], v[118:133]
	s_waitcnt vmcnt(9)
	ds_write_b128 v247, v[240:243] offset:5120
	global_load_dwordx4 v[240:243], v235, s[100:101]
	v_exp_f32_e32 v142, v142
	v_exp_f32_e32 v143, v143
	v_add_f32_e32 v0, v0, v142
	v_add_f32_e32 v0, v0, v143
	s_waitcnt lgkmcnt(5)
	v_mfma_f32_32x32x16_bf16 v[118:133], v[154:157], v[50:53], v[118:133]
	v_exp_f32_e32 v144, v144
	v_exp_f32_e32 v145, v145
	v_add_f32_e32 v0, v0, v144
	v_add_f32_e32 v0, v0, v145
	v_mfma_f32_32x32x16_bf16 v[54:69], v[170:173], v[134:137], v[54:69]
	ds_read_b128 v[170:173], v213 offset:23072
	v_exp_f32_e32 v146, v146
	v_exp_f32_e32 v147, v147
	v_add_f32_e32 v0, v0, v146
	v_mfma_f32_32x32x16_bf16 v[70:85], v[174:177], v[134:137], v[70:85]
	ds_read_b128 v[174:177], v213 offset:25632
	v_add_f32_e32 v0, v0, v147
	v_exp_f32_e32 v148, v148
	v_exp_f32_e32 v149, v149
	v_mfma_f32_32x32x16_bf16 v[86:101], v[178:181], v[134:137], v[86:101]
	ds_read_b128 v[178:181], v213 offset:28192
	v_add_f32_e32 v0, v0, v148
	v_add_f32_e32 v0, v0, v149
	v_cvt_pk_bf16_f32 v142, v142, v143
	v_mfma_f32_32x32x16_bf16 v[102:117], v[182:185], v[134:137], v[102:117]
	ds_read_b128 v[182:185], v213 offset:30752
	v_cvt_pk_bf16_f32 v143, v144, v145
	v_cvt_pk_bf16_f32 v144, v146, v147
	v_cvt_pk_bf16_f32 v145, v148, v149
	s_waitcnt lgkmcnt(3)
	s_nop 1
	v_mfma_f32_32x32x16_bf16 v[54:69], v[170:173], v[142:145], v[54:69]
	s_add_u32 s56, s56, 0x3000
	s_addc_u32 s57, s57, 0
	s_waitcnt lgkmcnt(2)
	v_mfma_f32_32x32x16_bf16 v[70:85], v[174:177], v[142:145], v[70:85]
	s_add_u32 s98, s98, 0x3000
	s_addc_u32 s99, s99, 0
	s_waitcnt lgkmcnt(1)
	v_mfma_f32_32x32x16_bf16 v[86:101], v[178:181], v[142:145], v[86:101]
	s_add_u32 s52, s52, 64
	s_addc_u32 s53, s53, 0
	s_waitcnt lgkmcnt(0)
	v_mfma_f32_32x32x16_bf16 v[102:117], v[182:185], v[142:145], v[102:117]
	s_add_u32 s100, s100, 64
	s_addc_u32 s101, s101, 0
	s_waitcnt lgkmcnt(0)
	s_barrier
; __device__ __forceinline__ void attn_item(const Params& p, int b, int h, int qt, float shift, unsigned char* smem) {
;     ...
;   ATT_STEP(sB, sA, ntile - 1);
;   {
;     bf16x8 vfr[4];
;     ATT_VLOAD((ntile - 1) % 3, 0);
;     ATT_SHIFT(sB);
;     ATT_FINISH(sB, (ntile - 1) % 3);
	ds_read_b128 v[150:153], v212 offset:0
	ds_read_b128 v[154:157], v212 offset:32
	ds_read_b128 v[158:161], v212 offset:64
	ds_read_b128 v[162:165], v212 offset:96
	ds_read_b128 v[166:169], v212 offset:128
	s_waitcnt lgkmcnt(4)
	v_mfma_f32_32x32x16_bf16 v[134:149], v[150:153], v[6:9], 0
	ds_read_b128 v[150:153], v212 offset:160
	ds_read_b128 v[170:173], v213 offset:46080
	s_waitcnt lgkmcnt(5)
	v_mfma_f32_32x32x16_bf16 v[134:149], v[154:157], v[10:13], v[134:149]
	ds_read_b128 v[154:157], v212 offset:192
	ds_read_b128 v[174:177], v213 offset:48640
	s_waitcnt lgkmcnt(6)
	v_mfma_f32_32x32x16_bf16 v[134:149], v[158:161], v[14:17], v[134:149]
	ds_read_b128 v[158:161], v212 offset:224
	ds_read_b128 v[178:181], v213 offset:51200
	s_waitcnt lgkmcnt(7)
	v_mfma_f32_32x32x16_bf16 v[134:149], v[162:165], v[18:21], v[134:149]
	ds_read_b128 v[162:165], v212 offset:256
	ds_read_b128 v[182:185], v213 offset:53760
	s_waitcnt lgkmcnt(8)
	v_mfma_f32_32x32x16_bf16 v[134:149], v[166:169], v[22:25], v[134:149]
	ds_read_b128 v[166:169], v212 offset:288
	v_exp_f32_e32 v118, v118
	v_exp_f32_e32 v119, v119
	v_add_f32_e32 v0, v0, v118
	s_waitcnt lgkmcnt(8)
	v_mfma_f32_32x32x16_bf16 v[134:149], v[150:153], v[26:29], v[134:149]
	ds_read_b128 v[150:153], v212 offset:320
	v_add_f32_e32 v0, v0, v119
	v_exp_f32_e32 v120, v120
	v_exp_f32_e32 v121, v121
	s_waitcnt lgkmcnt(7)
	v_mfma_f32_32x32x16_bf16 v[134:149], v[154:157], v[30:33], v[134:149]
	ds_read_b128 v[154:157], v212 offset:352
	s_waitcnt vmcnt(9)
	ds_write_b128 v244, v[188:191] offset:23040
	v_add_f32_e32 v0, v0, v120
	v_add_f32_e32 v0, v0, v121
	v_exp_f32_e32 v122, v122
	s_waitcnt lgkmcnt(7)
	v_mfma_f32_32x32x16_bf16 v[134:149], v[158:161], v[34:37], v[134:149]
	s_waitcnt vmcnt(8)
	ds_write_b128 v245, v[192:195] offset:23040
	v_exp_f32_e32 v123, v123
	v_add_f32_e32 v0, v0, v122
	v_add_f32_e32 v0, v0, v123
	s_waitcnt lgkmcnt(6)
	v_mfma_f32_32x32x16_bf16 v[134:149], v[162:165], v[38:41], v[134:149]
	s_waitcnt vmcnt(7)
	ds_write_b128 v246, v[196:199] offset:23040
	v_exp_f32_e32 v124, v124
	v_exp_f32_e32 v125, v125
	v_add_f32_e32 v0, v0, v124
	v_add_f32_e32 v0, v0, v125
	s_waitcnt lgkmcnt(5)
	v_mfma_f32_32x32x16_bf16 v[134:149], v[166:169], v[42:45], v[134:149]
	s_waitcnt vmcnt(6)
	ds_write_b128 v247, v[200:203] offset:23040
	v_cvt_pk_bf16_f32 v118, v118, v119
	v_cvt_pk_bf16_f32 v119, v120, v121
	v_cvt_pk_bf16_f32 v120, v122, v123
	v_cvt_pk_bf16_f32 v121, v124, v125
	s_waitcnt lgkmcnt(5)
	v_mfma_f32_32x32x16_bf16 v[134:149], v[150:153], v[46:49], v[134:149]
	s_waitcnt vmcnt(5)
	ds_write_b128 v247, v[204:207] offset:28160
	v_exp_f32_e32 v126, v126
	v_exp_f32_e32 v127, v127
	v_add_f32_e32 v0, v0, v126
	v_add_f32_e32 v0, v0, v127
	s_waitcnt lgkmcnt(5)
	v_mfma_f32_32x32x16_bf16 v[134:149], v[154:157], v[50:53], v[134:149]
	v_exp_f32_e32 v128, v128
	v_exp_f32_e32 v129, v129
	v_add_f32_e32 v0, v0, v128
	v_add_f32_e32 v0, v0, v129
	v_mfma_f32_32x32x16_bf16 v[54:69], v[170:173], v[118:121], v[54:69]
	ds_read_b128 v[170:173], v213 offset:46112
	v_exp_f32_e32 v130, v130
	v_exp_f32_e32 v131, v131
	v_add_f32_e32 v0, v0, v130
	v_mfma_f32_32x32x16_bf16 v[70:85], v[174:177], v[118:121], v[70:85]
	ds_read_b128 v[174:177], v213 offset:48672
	v_add_f32_e32 v0, v0, v131
	v_exp_f32_e32 v132, v132
	v_exp_f32_e32 v133, v133
	v_mfma_f32_32x32x16_bf16 v[86:101], v[178:181], v[118:121], v[86:101]
	ds_read_b128 v[178:181], v213 offset:51232
	v_add_f32_e32 v0, v0, v132
	v_add_f32_e32 v0, v0, v133
	v_cvt_pk_bf16_f32 v126, v126, v127
	v_mfma_f32_32x32x16_bf16 v[102:117], v[182:185], v[118:121], v[102:117]
	ds_read_b128 v[182:185], v213 offset:53792
	v_cvt_pk_bf16_f32 v127, v128, v129
	v_cvt_pk_bf16_f32 v128, v130, v131
	v_cvt_pk_bf16_f32 v129, v132, v133
	s_waitcnt lgkmcnt(3)
	s_nop 1
	v_mfma_f32_32x32x16_bf16 v[54:69], v[170:173], v[126:129], v[54:69]
	s_waitcnt lgkmcnt(2)
	v_mfma_f32_32x32x16_bf16 v[70:85], v[174:177], v[126:129], v[70:85]
	s_waitcnt lgkmcnt(1)
	v_mfma_f32_32x32x16_bf16 v[86:101], v[178:181], v[126:129], v[86:101]
	s_waitcnt lgkmcnt(0)
	v_mfma_f32_32x32x16_bf16 v[102:117], v[182:185], v[126:129], v[102:117]
	s_waitcnt lgkmcnt(0)
	s_barrier
	ds_read_b128 v[150:153], v212 offset:23040
	ds_read_b128 v[154:157], v212 offset:23072
	ds_read_b128 v[158:161], v212 offset:23104
	ds_read_b128 v[162:165], v212 offset:23136
	ds_read_b128 v[166:169], v212 offset:23168
	s_waitcnt lgkmcnt(4)
	v_mfma_f32_32x32x16_bf16 v[118:133], v[150:153], v[6:9], 0
	ds_read_b128 v[150:153], v212 offset:23200
	ds_read_b128 v[170:173], v213 offset:0
	s_waitcnt lgkmcnt(5)
	v_mfma_f32_32x32x16_bf16 v[118:133], v[154:157], v[10:13], v[118:133]
	ds_read_b128 v[154:157], v212 offset:23232
	ds_read_b128 v[174:177], v213 offset:2560
	s_waitcnt lgkmcnt(6)
	v_mfma_f32_32x32x16_bf16 v[118:133], v[158:161], v[14:17], v[118:133]
	ds_read_b128 v[158:161], v212 offset:23264
	ds_read_b128 v[178:181], v213 offset:5120
	s_waitcnt lgkmcnt(7)
	v_mfma_f32_32x32x16_bf16 v[118:133], v[162:165], v[18:21], v[118:133]
	ds_read_b128 v[162:165], v212 offset:23296
	ds_read_b128 v[182:185], v213 offset:7680
	s_waitcnt lgkmcnt(8)
	v_mfma_f32_32x32x16_bf16 v[118:133], v[166:169], v[22:25], v[118:133]
	ds_read_b128 v[166:169], v212 offset:23328
	v_exp_f32_e32 v134, v134
	v_exp_f32_e32 v135, v135
	v_add_f32_e32 v0, v0, v134
	s_waitcnt lgkmcnt(8)
	v_mfma_f32_32x32x16_bf16 v[118:133], v[150:153], v[26:29], v[118:133]
	ds_read_b128 v[150:153], v212 offset:23360
	v_add_f32_e32 v0, v0, v135
	v_exp_f32_e32 v136, v136
	v_exp_f32_e32 v137, v137
	s_waitcnt lgkmcnt(7)
	v_mfma_f32_32x32x16_bf16 v[118:133], v[154:157], v[30:33], v[118:133]
	ds_read_b128 v[154:157], v212 offset:23392
	s_waitcnt vmcnt(4)
; __device__ __forceinline__ void attn_item(const Params& p, int b, int h, int qt, float shift, unsigned char* smem) {
;     ...
;   ATT_STEP(sB, sA, ntile - 1);
;   {
;     bf16x8 vfr[4];
;     ATT_VLOAD((ntile - 1) % 3, 0);
;     ATT_SHIFT(sB);
;     ATT_FINISH(sB, (ntile - 1) % 3);
;   }
	ds_write_b128 v244, v[208:211] offset:46080
	v_add_f32_e32 v0, v0, v136
	v_add_f32_e32 v0, v0, v137
	v_exp_f32_e32 v138, v138
	s_waitcnt lgkmcnt(7)
	v_mfma_f32_32x32x16_bf16 v[118:133], v[158:161], v[34:37], v[118:133]
	s_waitcnt vmcnt(3)
	ds_write_b128 v245, v[216:219] offset:46080
	v_exp_f32_e32 v139, v139
	v_add_f32_e32 v0, v0, v138
	v_add_f32_e32 v0, v0, v139
	s_waitcnt lgkmcnt(6)
	v_mfma_f32_32x32x16_bf16 v[118:133], v[162:165], v[38:41], v[118:133]
	s_waitcnt vmcnt(2)
	ds_write_b128 v246, v[220:223] offset:46080
	v_exp_f32_e32 v140, v140
	v_exp_f32_e32 v141, v141
	v_add_f32_e32 v0, v0, v140
	v_add_f32_e32 v0, v0, v141
	s_waitcnt lgkmcnt(5)
	v_mfma_f32_32x32x16_bf16 v[118:133], v[166:169], v[42:45], v[118:133]
	s_waitcnt vmcnt(1)
	ds_write_b128 v247, v[236:239] offset:46080
	v_cvt_pk_bf16_f32 v134, v134, v135
	v_cvt_pk_bf16_f32 v135, v136, v137
	v_cvt_pk_bf16_f32 v136, v138, v139
	v_cvt_pk_bf16_f32 v137, v140, v141
	s_waitcnt lgkmcnt(5)
	v_mfma_f32_32x32x16_bf16 v[118:133], v[150:153], v[46:49], v[118:133]
	s_waitcnt vmcnt(0)
	ds_write_b128 v247, v[240:243] offset:51200
	v_exp_f32_e32 v142, v142
	v_exp_f32_e32 v143, v143
	v_add_f32_e32 v0, v0, v142
	v_add_f32_e32 v0, v0, v143
	s_waitcnt lgkmcnt(5)
	v_mfma_f32_32x32x16_bf16 v[118:133], v[154:157], v[50:53], v[118:133]
	v_exp_f32_e32 v144, v144
	v_exp_f32_e32 v145, v145
	v_add_f32_e32 v0, v0, v144
	v_add_f32_e32 v0, v0, v145
	v_mfma_f32_32x32x16_bf16 v[54:69], v[170:173], v[134:137], v[54:69]
	ds_read_b128 v[170:173], v213 offset:32
	v_exp_f32_e32 v146, v146
	v_exp_f32_e32 v147, v147
	v_add_f32_e32 v0, v0, v146
	v_mfma_f32_32x32x16_bf16 v[70:85], v[174:177], v[134:137], v[70:85]
	ds_read_b128 v[174:177], v213 offset:2592
	v_add_f32_e32 v0, v0, v147
	v_exp_f32_e32 v148, v148
	v_exp_f32_e32 v149, v149
	v_mfma_f32_32x32x16_bf16 v[86:101], v[178:181], v[134:137], v[86:101]
	ds_read_b128 v[178:181], v213 offset:5152
	v_add_f32_e32 v0, v0, v148
	v_add_f32_e32 v0, v0, v149
	v_cvt_pk_bf16_f32 v142, v142, v143
	v_mfma_f32_32x32x16_bf16 v[102:117], v[182:185], v[134:137], v[102:117]
	ds_read_b128 v[182:185], v213 offset:7712
	v_cvt_pk_bf16_f32 v143, v144, v145
	v_cvt_pk_bf16_f32 v144, v146, v147
	v_cvt_pk_bf16_f32 v145, v148, v149
	s_waitcnt lgkmcnt(3)
	s_nop 1
	v_mfma_f32_32x32x16_bf16 v[54:69], v[170:173], v[142:145], v[54:69]
	s_waitcnt lgkmcnt(2)
	v_mfma_f32_32x32x16_bf16 v[70:85], v[174:177], v[142:145], v[70:85]
	s_waitcnt lgkmcnt(1)
	v_mfma_f32_32x32x16_bf16 v[86:101], v[178:181], v[142:145], v[86:101]
	s_waitcnt lgkmcnt(0)
	v_mfma_f32_32x32x16_bf16 v[102:117], v[182:185], v[142:145], v[102:117]
	s_waitcnt lgkmcnt(0)
	s_barrier
	ds_read_b128 v[150:153], v212 offset:46080
	ds_read_b128 v[154:157], v212 offset:46112
	ds_read_b128 v[158:161], v212 offset:46144
	ds_read_b128 v[162:165], v212 offset:46176
	ds_read_b128 v[166:169], v212 offset:46208
	s_waitcnt lgkmcnt(4)
	v_mfma_f32_32x32x16_bf16 v[134:149], v[150:153], v[6:9], 0
	ds_read_b128 v[150:153], v212 offset:46240
	ds_read_b128 v[170:173], v213 offset:23040
	s_waitcnt lgkmcnt(5)
	v_mfma_f32_32x32x16_bf16 v[134:149], v[154:157], v[10:13], v[134:149]
	ds_read_b128 v[154:157], v212 offset:46272
	ds_read_b128 v[174:177], v213 offset:25600
	s_waitcnt lgkmcnt(6)
	v_mfma_f32_32x32x16_bf16 v[134:149], v[158:161], v[14:17], v[134:149]
	ds_read_b128 v[158:161], v212 offset:46304
	ds_read_b128 v[178:181], v213 offset:28160
	s_waitcnt lgkmcnt(7)
	v_mfma_f32_32x32x16_bf16 v[134:149], v[162:165], v[18:21], v[134:149]
	ds_read_b128 v[162:165], v212 offset:46336
	ds_read_b128 v[182:185], v213 offset:30720
	s_waitcnt lgkmcnt(8)
	v_mfma_f32_32x32x16_bf16 v[134:149], v[166:169], v[22:25], v[134:149]
	ds_read_b128 v[166:169], v212 offset:46368
	v_exp_f32_e32 v118, v118
	v_exp_f32_e32 v119, v119
	v_add_f32_e32 v0, v0, v118
	s_waitcnt lgkmcnt(8)
	v_mfma_f32_32x32x16_bf16 v[134:149], v[150:153], v[26:29], v[134:149]
	ds_read_b128 v[150:153], v212 offset:46400
	v_add_f32_e32 v0, v0, v119
	v_exp_f32_e32 v120, v120
	v_exp_f32_e32 v121, v121
	s_waitcnt lgkmcnt(7)
	v_mfma_f32_32x32x16_bf16 v[134:149], v[154:157], v[30:33], v[134:149]
	ds_read_b128 v[154:157], v212 offset:46432
	v_add_f32_e32 v0, v0, v120
	v_add_f32_e32 v0, v0, v121
	v_exp_f32_e32 v122, v122
	s_waitcnt lgkmcnt(6)
	v_mfma_f32_32x32x16_bf16 v[134:149], v[158:161], v[34:37], v[134:149]
	v_exp_f32_e32 v123, v123
	v_add_f32_e32 v0, v0, v122
	v_add_f32_e32 v0, v0, v123
	s_waitcnt lgkmcnt(4)
	v_mfma_f32_32x32x16_bf16 v[134:149], v[162:165], v[38:41], v[134:149]
	v_exp_f32_e32 v124, v124
	v_exp_f32_e32 v125, v125
	v_add_f32_e32 v0, v0, v124
	v_add_f32_e32 v0, v0, v125
	s_waitcnt lgkmcnt(2)
	v_mfma_f32_32x32x16_bf16 v[134:149], v[166:169], v[42:45], v[134:149]
	v_cvt_pk_bf16_f32 v118, v118, v119
	v_cvt_pk_bf16_f32 v119, v120, v121
	v_cvt_pk_bf16_f32 v120, v122, v123
	v_cvt_pk_bf16_f32 v121, v124, v125
	s_waitcnt lgkmcnt(1)
	v_mfma_f32_32x32x16_bf16 v[134:149], v[150:153], v[46:49], v[134:149]
	v_exp_f32_e32 v126, v126
	v_exp_f32_e32 v127, v127
	v_add_f32_e32 v0, v0, v126
	v_add_f32_e32 v0, v0, v127
	s_waitcnt lgkmcnt(0)
	v_mfma_f32_32x32x16_bf16 v[134:149], v[154:157], v[50:53], v[134:149]
	v_exp_f32_e32 v128, v128
	v_exp_f32_e32 v129, v129
	v_add_f32_e32 v0, v0, v128
	v_add_f32_e32 v0, v0, v129
	v_mfma_f32_32x32x16_bf16 v[54:69], v[170:173], v[118:121], v[54:69]
	ds_read_b128 v[170:173], v213 offset:23072
	v_exp_f32_e32 v130, v130
	v_exp_f32_e32 v131, v131
	v_add_f32_e32 v0, v0, v130
	v_mfma_f32_32x32x16_bf16 v[70:85], v[174:177], v[118:121], v[70:85]
	ds_read_b128 v[174:177], v213 offset:25632
	v_add_f32_e32 v0, v0, v131
	v_exp_f32_e32 v132, v132
	v_exp_f32_e32 v133, v133
	v_mfma_f32_32x32x16_bf16 v[86:101], v[178:181], v[118:121], v[86:101]
	ds_read_b128 v[178:181], v213 offset:28192
	v_add_f32_e32 v0, v0, v132
	v_add_f32_e32 v0, v0, v133
	v_cvt_pk_bf16_f32 v126, v126, v127
	v_mfma_f32_32x32x16_bf16 v[102:117], v[182:185], v[118:121], v[102:117]
	ds_read_b128 v[182:185], v213 offset:30752
	v_cvt_pk_bf16_f32 v127, v128, v129
	v_cvt_pk_bf16_f32 v128, v130, v131
	v_cvt_pk_bf16_f32 v129, v132, v133
	s_waitcnt lgkmcnt(3)
	s_nop 1
	v_mfma_f32_32x32x16_bf16 v[54:69], v[170:173], v[126:129], v[54:69]
	s_waitcnt lgkmcnt(2)
	v_mfma_f32_32x32x16_bf16 v[70:85], v[174:177], v[126:129], v[70:85]
	s_waitcnt lgkmcnt(1)
	v_mfma_f32_32x32x16_bf16 v[86:101], v[178:181], v[126:129], v[86:101]
	s_waitcnt lgkmcnt(0)
	v_mfma_f32_32x32x16_bf16 v[102:117], v[182:185], v[126:129], v[102:117]
	s_waitcnt lgkmcnt(0)
	s_barrier
; __device__ __forceinline__ void attn_item(const Params& p, int b, int h, int qt, float shift, unsigned char* smem) {
;     ...
;   {
;     bf16x8 vfr[4];
;     ATT_VLOAD((ntile - 1) % 3, 0);
;     ATT_SHIFT(sB);
;     ATT_FINISH(sB, (ntile - 1) % 3);
;   }
;   __syncthreads();
;     ...
; #pragma unroll
;   for (int qi = 0; qi < 2; ++qi) {
;     float ls = qi ? lrun1 : lrun0;
;     ls += __shfl_xor(ls, 16);
;     ls += __shfl_xor(ls, 32);
;     const float inv = 1.f / ls;
;     const int pos = qt * 128 + wid * 32 + qi * 16 + l16;
;     const int row = (pos < CTX) ? (T_LAT + b * CTX + pos) : (b * SEQ + pos - CTX);
;     u16* orow = p.YM + (size_t)row * 1024 + 512 + h * 128 + quad * 4;
; #pragma unroll
;     for (int vt = 0; vt < 8; ++vt) {
;       u32x2 pk;
;       pk.x = pack2(o[vt][qi][0] * inv, o[vt][qi][1] * inv);
;       pk.y = pack2(o[vt][qi][2] * inv, o[vt][qi][3] * inv);
;       *(u32x2*)(orow + vt * 16) = pk;
;     }
;   }
	ds_read_b128 v[170:173], v213 offset:46080
	ds_read_b128 v[174:177], v213 offset:48640
	ds_read_b128 v[178:181], v213 offset:51200
	ds_read_b128 v[182:185], v213 offset:53760
	v_exp_f32_e32 v134, v134
	v_exp_f32_e32 v135, v135
	v_add_f32_e32 v0, v0, v134
	v_add_f32_e32 v0, v0, v135
	v_exp_f32_e32 v136, v136
	v_exp_f32_e32 v137, v137
	v_add_f32_e32 v0, v0, v136
	v_add_f32_e32 v0, v0, v137
	v_exp_f32_e32 v138, v138
	v_exp_f32_e32 v139, v139
	v_add_f32_e32 v0, v0, v138
	v_add_f32_e32 v0, v0, v139
	v_exp_f32_e32 v140, v140
	v_exp_f32_e32 v141, v141
	v_add_f32_e32 v0, v0, v140
	v_add_f32_e32 v0, v0, v141
	v_cvt_pk_bf16_f32 v134, v134, v135
	v_cvt_pk_bf16_f32 v135, v136, v137
	v_cvt_pk_bf16_f32 v136, v138, v139
	v_cvt_pk_bf16_f32 v137, v140, v141
	v_exp_f32_e32 v142, v142
	v_exp_f32_e32 v143, v143
	v_add_f32_e32 v0, v0, v142
	v_add_f32_e32 v0, v0, v143
	v_exp_f32_e32 v144, v144
	v_exp_f32_e32 v145, v145
	v_add_f32_e32 v0, v0, v144
	v_add_f32_e32 v0, v0, v145
	v_exp_f32_e32 v146, v146
	v_exp_f32_e32 v147, v147
	v_add_f32_e32 v0, v0, v146
	v_add_f32_e32 v0, v0, v147
	v_exp_f32_e32 v148, v148
	v_exp_f32_e32 v149, v149
	v_add_f32_e32 v0, v0, v148
	v_add_f32_e32 v0, v0, v149
	v_cvt_pk_bf16_f32 v142, v142, v143
	v_cvt_pk_bf16_f32 v143, v144, v145
	v_cvt_pk_bf16_f32 v144, v146, v147
	v_cvt_pk_bf16_f32 v145, v148, v149
	s_nop 1
	s_waitcnt lgkmcnt(3)
	v_mfma_f32_32x32x16_bf16 v[54:69], v[170:173], v[134:137], v[54:69]
	ds_read_b128 v[170:173], v213 offset:46112
	s_waitcnt lgkmcnt(3)
	v_mfma_f32_32x32x16_bf16 v[70:85], v[174:177], v[134:137], v[70:85]
	ds_read_b128 v[174:177], v213 offset:48672
	s_waitcnt lgkmcnt(3)
	v_mfma_f32_32x32x16_bf16 v[86:101], v[178:181], v[134:137], v[86:101]
	ds_read_b128 v[178:181], v213 offset:51232
	s_waitcnt lgkmcnt(3)
	v_mfma_f32_32x32x16_bf16 v[102:117], v[182:185], v[134:137], v[102:117]
	ds_read_b128 v[182:185], v213 offset:53792
	s_waitcnt lgkmcnt(3)
	v_mfma_f32_32x32x16_bf16 v[54:69], v[170:173], v[142:145], v[54:69]
	s_waitcnt lgkmcnt(2)
	v_mfma_f32_32x32x16_bf16 v[70:85], v[174:177], v[142:145], v[70:85]
	s_waitcnt lgkmcnt(1)
	v_mfma_f32_32x32x16_bf16 v[86:101], v[178:181], v[142:145], v[86:101]
	s_waitcnt lgkmcnt(0)
	v_mfma_f32_32x32x16_bf16 v[102:117], v[182:185], v[142:145], v[102:117]
	ds_bpermute_b32 v118, v229, v0
	v_and_b32_e32 v119, 31, v187
	v_bfe_u32 v120, v187, 5, 1
	v_lshlrev_b32_e32 v119, 11, v119
	v_lshl_add_u32 v123, v120, 3, v119
	s_waitcnt lgkmcnt(0)
	v_add_f32_e32 v0, v0, v118
	v_div_scale_f32 v118, s[0:1], v0, v0, 1.0
	v_rcp_f32_e32 v119, v118
	s_nop 0
	v_fma_f32 v120, -v118, v119, 1.0
	v_fmac_f32_e32 v119, v120, v119
	v_div_scale_f32 v120, vcc, 1.0, v0, 1.0
	v_mul_f32_e32 v121, v120, v119
	v_fma_f32 v122, -v118, v121, v120
	v_fmac_f32_e32 v121, v122, v119
	v_fma_f32 v118, -v118, v121, v120
	v_div_fmas_f32 v118, v118, v119, v121
	v_div_fixup_f32 v0, v118, v0, 1.0
	s_nop 4
	v_mul_f32_e32 v54, v54, v0
	v_mul_f32_e32 v55, v55, v0
	v_mul_f32_e32 v56, v56, v0
	v_mul_f32_e32 v57, v57, v0
	v_cvt_pk_bf16_f32 v54, v54, v55
	v_cvt_pk_bf16_f32 v55, v56, v57
	global_store_dwordx2 v123, v[54:55], s[88:89] offset:0
	v_mul_f32_e32 v58, v58, v0
	v_mul_f32_e32 v59, v59, v0
	v_mul_f32_e32 v60, v60, v0
	v_mul_f32_e32 v61, v61, v0
	v_cvt_pk_bf16_f32 v58, v58, v59
	v_cvt_pk_bf16_f32 v59, v60, v61
	global_store_dwordx2 v123, v[58:59], s[88:89] offset:16
	v_mul_f32_e32 v62, v62, v0
	v_mul_f32_e32 v63, v63, v0
	v_mul_f32_e32 v64, v64, v0
	v_mul_f32_e32 v65, v65, v0
	v_cvt_pk_bf16_f32 v62, v62, v63
	v_cvt_pk_bf16_f32 v63, v64, v65
	global_store_dwordx2 v123, v[62:63], s[88:89] offset:32
	v_mul_f32_e32 v66, v66, v0
	v_mul_f32_e32 v67, v67, v0
	v_mul_f32_e32 v68, v68, v0
	v_mul_f32_e32 v69, v69, v0
	v_cvt_pk_bf16_f32 v66, v66, v67
	v_cvt_pk_bf16_f32 v67, v68, v69
	global_store_dwordx2 v123, v[66:67], s[88:89] offset:48
	v_mul_f32_e32 v70, v70, v0
	v_mul_f32_e32 v71, v71, v0
	v_mul_f32_e32 v72, v72, v0
	v_mul_f32_e32 v73, v73, v0
	v_cvt_pk_bf16_f32 v70, v70, v71
	v_cvt_pk_bf16_f32 v71, v72, v73
	global_store_dwordx2 v123, v[70:71], s[88:89] offset:64
	v_mul_f32_e32 v74, v74, v0
	v_mul_f32_e32 v75, v75, v0
	v_mul_f32_e32 v76, v76, v0
	v_mul_f32_e32 v77, v77, v0
	v_cvt_pk_bf16_f32 v74, v74, v75
	v_cvt_pk_bf16_f32 v75, v76, v77
	global_store_dwordx2 v123, v[74:75], s[88:89] offset:80
	v_mul_f32_e32 v78, v78, v0
	v_mul_f32_e32 v79, v79, v0
	v_mul_f32_e32 v80, v80, v0
	v_mul_f32_e32 v81, v81, v0
	v_cvt_pk_bf16_f32 v78, v78, v79
	v_cvt_pk_bf16_f32 v79, v80, v81
	global_store_dwordx2 v123, v[78:79], s[88:89] offset:96
	v_mul_f32_e32 v82, v82, v0
	v_mul_f32_e32 v83, v83, v0
	v_mul_f32_e32 v84, v84, v0
	v_mul_f32_e32 v85, v85, v0
	v_cvt_pk_bf16_f32 v82, v82, v83
	v_cvt_pk_bf16_f32 v83, v84, v85
	global_store_dwordx2 v123, v[82:83], s[88:89] offset:112
	v_mul_f32_e32 v86, v86, v0
	v_mul_f32_e32 v87, v87, v0
	v_mul_f32_e32 v88, v88, v0
	v_mul_f32_e32 v89, v89, v0
	v_cvt_pk_bf16_f32 v86, v86, v87
	v_cvt_pk_bf16_f32 v87, v88, v89
	global_store_dwordx2 v123, v[86:87], s[88:89] offset:128
	v_mul_f32_e32 v90, v90, v0
	v_mul_f32_e32 v91, v91, v0
	v_mul_f32_e32 v92, v92, v0
	v_mul_f32_e32 v93, v93, v0
	v_cvt_pk_bf16_f32 v90, v90, v91
	v_cvt_pk_bf16_f32 v91, v92, v93
	global_store_dwordx2 v123, v[90:91], s[88:89] offset:144
	v_mul_f32_e32 v94, v94, v0
	v_mul_f32_e32 v95, v95, v0
	v_mul_f32_e32 v96, v96, v0
	v_mul_f32_e32 v97, v97, v0
	v_cvt_pk_bf16_f32 v94, v94, v95
	v_cvt_pk_bf16_f32 v95, v96, v97
	global_store_dwordx2 v123, v[94:95], s[88:89] offset:160
	v_mul_f32_e32 v98, v98, v0
	v_mul_f32_e32 v99, v99, v0
	v_mul_f32_e32 v100, v100, v0
	v_mul_f32_e32 v101, v101, v0
	v_cvt_pk_bf16_f32 v98, v98, v99
	v_cvt_pk_bf16_f32 v99, v100, v101
	global_store_dwordx2 v123, v[98:99], s[88:89] offset:176
	v_mul_f32_e32 v102, v102, v0
	v_mul_f32_e32 v103, v103, v0
	v_mul_f32_e32 v104, v104, v0
	v_mul_f32_e32 v105, v105, v0
	v_cvt_pk_bf16_f32 v102, v102, v103
	v_cvt_pk_bf16_f32 v103, v104, v105
	global_store_dwordx2 v123, v[102:103], s[88:89] offset:192
	v_mul_f32_e32 v106, v106, v0
	v_mul_f32_e32 v107, v107, v0
	v_mul_f32_e32 v108, v108, v0
	v_mul_f32_e32 v109, v109, v0
	v_cvt_pk_bf16_f32 v106, v106, v107
	v_cvt_pk_bf16_f32 v107, v108, v109
	global_store_dwordx2 v123, v[106:107], s[88:89] offset:208
	v_mul_f32_e32 v110, v110, v0
	v_mul_f32_e32 v111, v111, v0
	v_mul_f32_e32 v112, v112, v0
	v_mul_f32_e32 v113, v113, v0
	v_cvt_pk_bf16_f32 v110, v110, v111
	v_cvt_pk_bf16_f32 v111, v112, v113
	global_store_dwordx2 v123, v[110:111], s[88:89] offset:224
	v_mul_f32_e32 v114, v114, v0
	v_mul_f32_e32 v115, v115, v0
	v_mul_f32_e32 v116, v116, v0
	v_mul_f32_e32 v117, v117, v0
	v_cvt_pk_bf16_f32 v114, v114, v115
	v_cvt_pk_bf16_f32 v115, v116, v117
	global_store_dwordx2 v123, v[114:115], s[88:89] offset:240
	s_waitcnt lgkmcnt(0)
	s_barrier
	s_mov_b32 s47, s95
	s_add_i32 s50, s50, s3
	s_cmp_gt_i32 s50, 63
	s_cbranch_scc0 .LBB0_766
	s_branch .LBB0_776

